# second attention loop: dropped the m0 save/restore SALU pairs around its 8 LDS-DMA issues
# baseline (speedup 1.0000x reference)
; #define LAS __attribute__((address_space(3)))
; #define MFMA32(a, b, c) __builtin_amdgcn_mfma_f32_32x32x16_bf16((a), (b), (c), 0, 0, 0)
; DI void attn_unit(const bf16_t* Q, const bf16_t* Kp, const bf16_t* Vp, bf16_t* O, size_t qrow0, size_t krow0, int ntile, int h, float lam, float lam_init, const float* gsub, LAS unsigned char* lds) {
;     ...
;     for (int t = 0; t < ntile; t += 2) {
;       {
;         { const int tk = (t + 4 < ntile) ? t + 4 : ntile - 1; AT_ISSUE_K(tk, ks0); const int tv = (t + 2 < ntile) ? t + 2 : ntile - 1; AT_ISSUE_V(tv, vs1); }
;         LAS unsigned char* kb = lds + KRING + ks1 * SLOT + kro;
;         LAS unsigned char* vb = lds + VRING + vsm1 * SLOT + vro;
;         __builtin_amdgcn_s_setprio(1);
;         { bf16x8 ql[4];
; #pragma unroll
;           for (int d0 = 0; d0 < 4; ++d0) ql[d0] = qf[d0];
; #pragma unroll
;           for (int kh = 0; kh < 2; ++kh) {
;             bf16x8 kf[4];
; #pragma unroll
;             for (int e = 0; e < 4; ++e) kf[e] = *(const LAS bf16x8*)(kb + kh * 4096 + (((2 * e + hh) ^ ksw) * 16));
;             sn[kh] = MFMA32(kf[0], ql[0], negm);
; #pragma unroll
;             for (int d0 = 1; d0 < 4; ++d0) sn[kh] = MFMA32(kf[d0], ql[d0], sn[kh]);
;             __builtin_amdgcn_sched_barrier(0);
;           } }
; #pragma unroll
;         for (int j = 0; j < 4; ++j) {
;             s16x4 lo[4], hi[4];
; #pragma unroll
;             for (int e = 0; e < 4; ++e) { LAS unsigned char* vp = vb + j * 4096 + ((e ^ q4) * 64);
;                 lo[e] = __builtin_bit_cast(s16x4, __builtin_amdgcn_ds_read_tr16_b64_v4i16((LAS s16x4*)vp));
;                 hi[e] = __builtin_bit_cast(s16x4, __builtin_amdgcn_ds_read_tr16_b64_v4i16((LAS s16x4*)(vp + 2048))); }
; #pragma unroll
;             for (int e = 0; e < 4; ++e) ot[e] = MFMA32(__builtin_shufflevector(lo[e], hi[e], 0, 1, 2, 3, 4, 5, 6, 7), __builtin_bit_cast(bf16x8, pp[j]), ot[e]);
;             __builtin_amdgcn_sched_barrier(0);
;         }
;         __builtin_amdgcn_s_setprio(0);
;         if (!shifted) {
;             ps = 0.f;
; #pragma unroll
;             for (int kh = 0; kh < 2; ++kh)
; #pragma unroll
;                 for (int i = 0; i < 16; ++i) { sc[kh][i] = __builtin_amdgcn_exp2f(sc[kh][i]); ps += sc[kh][i]; }
;             l_run += ps;
;         }
.LBB0_551:
	s_lshl_b32 s73, s73, 14
	s_add_i32 s74, s73, s66
	s_add_i32 s73, s73, s69
	s_add_i32 s74, s74, 0
	s_mov_b32 m0, s74
	s_nop 0
	global_load_lds_dwordx4 v[198:199], off
	s_add_i32 s73, s73, 0
	s_mov_b32 m0, s73
	s_nop 0
	global_load_lds_dwordx4 v[200:201], off
	s_add_u32 s40, s46, s40
	s_addc_u32 s41, s47, s41
	s_lshl_b32 s74, s67, 14
	s_add_i32 s73, s70, s74
	s_add_i32 s73, s73, 0
	v_lshl_add_u64 v[114:115], s[40:41], 0, v[194:195]
	s_mov_b32 m0, s73
	s_nop 0
	global_load_lds_dwordx4 v[114:115], off
	s_add_i32 s73, s71, s74
	s_add_i32 s73, s73, 0
	v_lshl_add_u64 v[114:115], s[40:41], 0, v[196:197]
	s_mov_b32 m0, s73
	s_nop 0
	global_load_lds_dwordx4 v[114:115], off
	s_lshl_b32 s76, s72, 14
	s_lshl_b32 s75, s68, 14
	s_setprio 1
	v_add_u32_e32 v1, s76, v213
	v_add_u32_e32 v134, v1, v214
	ds_read_b128 v[130:133], v134
	v_add_u32_e32 v207, v1, v215
	v_add_u32_e32 v227, v1, v216
	v_add_u32_e32 v1, v1, v217
	s_waitcnt lgkmcnt(0)
	v_mfma_f32_32x32x16_bf16 v[114:129], v[130:133], v[146:149], v[98:113]
	ds_read_b128 v[130:133], v207
	s_waitcnt lgkmcnt(0)
	v_mfma_f32_32x32x16_bf16 v[114:129], v[130:133], v[150:153], v[114:129]
	ds_read_b128 v[130:133], v227
	s_waitcnt lgkmcnt(0)
	v_mfma_f32_32x32x16_bf16 v[114:129], v[130:133], v[154:157], v[114:129]
	ds_read_b128 v[130:133], v1
	s_waitcnt lgkmcnt(0)
	v_mfma_f32_32x32x16_bf16 v[114:129], v[130:133], v[158:161], v[114:129]
	ds_read_b128 v[182:185], v134 offset:4096
	s_waitcnt lgkmcnt(0)
	v_mfma_f32_32x32x16_bf16 v[130:145], v[182:185], v[146:149], v[98:113]
	ds_read_b128 v[182:185], v207 offset:4096
	s_waitcnt lgkmcnt(0)
	v_mfma_f32_32x32x16_bf16 v[130:145], v[182:185], v[150:153], v[130:145]
	ds_read_b128 v[182:185], v227 offset:4096
	s_waitcnt lgkmcnt(0)
	v_mfma_f32_32x32x16_bf16 v[130:145], v[182:185], v[154:157], v[130:145]
	ds_read_b128 v[182:185], v1 offset:4096
	s_waitcnt lgkmcnt(0)
	v_mfma_f32_32x32x16_bf16 v[130:145], v[182:185], v[158:161], v[130:145]
	v_add_u32_e32 v1, s75, v225
	v_add_u32_e32 v207, v1, v224
	v_add_u32_e32 v227, v1, v223
	ds_read_b64_tr_b16 v[182:183], v207
	ds_read_b64_tr_b16 v[184:185], v207 offset:2048
	ds_read_b64_tr_b16 v[228:229], v227
	ds_read_b64_tr_b16 v[230:231], v227 offset:2048
	v_add_u32_e32 v232, v1, v222
	v_add_u32_e32 v1, v1, v220
	s_waitcnt lgkmcnt(2)
	v_mfma_f32_32x32x16_bf16 v[50:65], v[182:185], v[174:177], v[50:65]
	ds_read_b64_tr_b16 v[182:183], v232
	ds_read_b64_tr_b16 v[184:185], v232 offset:2048
	s_waitcnt lgkmcnt(2)
	v_mfma_f32_32x32x16_bf16 v[34:49], v[228:231], v[174:177], v[34:49]
	ds_read_b64_tr_b16 v[228:229], v1
	ds_read_b64_tr_b16 v[230:231], v1 offset:2048
	s_waitcnt lgkmcnt(2)
	v_mfma_f32_32x32x16_bf16 v[18:33], v[182:185], v[174:177], v[18:33]
	s_waitcnt lgkmcnt(0)
	v_mfma_f32_32x32x16_bf16 v[2:17], v[228:231], v[174:177], v[2:17]
	ds_read_b64_tr_b16 v[174:175], v207 offset:4096
	ds_read_b64_tr_b16 v[176:177], v207 offset:6144
	ds_read_b64_tr_b16 v[182:183], v227 offset:4096
	ds_read_b64_tr_b16 v[184:185], v227 offset:6144
	s_waitcnt lgkmcnt(2)
	v_mfma_f32_32x32x16_bf16 v[50:65], v[174:177], v[170:173], v[50:65]
	s_waitcnt lgkmcnt(0)
	v_mfma_f32_32x32x16_bf16 v[34:49], v[182:185], v[170:173], v[34:49]
	ds_read_b64_tr_b16 v[174:175], v232 offset:4096
	ds_read_b64_tr_b16 v[176:177], v232 offset:6144
	ds_read_b64_tr_b16 v[182:183], v1 offset:4096
	ds_read_b64_tr_b16 v[184:185], v1 offset:6144
	s_waitcnt lgkmcnt(2)
	v_mfma_f32_32x32x16_bf16 v[18:33], v[174:177], v[170:173], v[18:33]
	s_waitcnt lgkmcnt(0)
	v_mfma_f32_32x32x16_bf16 v[2:17], v[182:185], v[170:173], v[2:17]
	ds_read_b64_tr_b16 v[170:171], v207 offset:8192
	ds_read_b64_tr_b16 v[172:173], v207 offset:10240
	ds_read_b64_tr_b16 v[174:175], v227 offset:8192
	ds_read_b64_tr_b16 v[176:177], v227 offset:10240
	s_waitcnt lgkmcnt(2)
	v_mfma_f32_32x32x16_bf16 v[50:65], v[170:173], v[166:169], v[50:65]
	s_waitcnt lgkmcnt(0)
	v_mfma_f32_32x32x16_bf16 v[34:49], v[174:177], v[166:169], v[34:49]
	ds_read_b64_tr_b16 v[170:171], v232 offset:8192
	ds_read_b64_tr_b16 v[172:173], v232 offset:10240
	ds_read_b64_tr_b16 v[174:175], v1 offset:8192
	ds_read_b64_tr_b16 v[176:177], v1 offset:10240
	s_waitcnt lgkmcnt(2)
	v_mfma_f32_32x32x16_bf16 v[18:33], v[170:173], v[166:169], v[18:33]
	s_waitcnt lgkmcnt(0)
	v_mfma_f32_32x32x16_bf16 v[2:17], v[174:177], v[166:169], v[2:17]
	ds_read_b64_tr_b16 v[166:167], v207 offset:12288
	ds_read_b64_tr_b16 v[168:169], v207 offset:14336
	ds_read_b64_tr_b16 v[170:171], v227 offset:12288
	ds_read_b64_tr_b16 v[172:173], v227 offset:14336
	s_waitcnt lgkmcnt(2)
	v_mfma_f32_32x32x16_bf16 v[50:65], v[166:169], v[162:165], v[50:65]
	s_waitcnt lgkmcnt(0)
	v_mfma_f32_32x32x16_bf16 v[34:49], v[170:173], v[162:165], v[34:49]
	ds_read_b64_tr_b16 v[166:167], v232 offset:12288
	ds_read_b64_tr_b16 v[168:169], v232 offset:14336
	ds_read_b64_tr_b16 v[170:171], v1 offset:12288
	ds_read_b64_tr_b16 v[172:173], v1 offset:14336
	s_waitcnt lgkmcnt(2)
	v_mfma_f32_32x32x16_bf16 v[18:33], v[166:169], v[162:165], v[18:33]
	s_waitcnt lgkmcnt(0)
	v_mfma_f32_32x32x16_bf16 v[2:17], v[170:173], v[162:165], v[2:17]
	s_setprio 0
	v_cndmask_b32_e64 v1, 0, 1, s[50:51]
	v_cmp_ne_u32_e64 s[40:41], 1, v1
	s_andn2_b64 vcc, exec, s[50:51]
	s_cbranch_vccnz .LBB0_553
	v_exp_f32_e32 v66, v66
	v_exp_f32_e32 v67, v67
	v_exp_f32_e32 v68, v68
	v_exp_f32_e32 v69, v69
	v_add_f32_e32 v1, 0, v66
	v_exp_f32_e32 v70, v70
	v_add_f32_e32 v1, v67, v1
	v_exp_f32_e32 v71, v71
	v_add_f32_e32 v1, v68, v1
	v_exp_f32_e32 v72, v72
	v_add_f32_e32 v1, v69, v1
	v_exp_f32_e32 v73, v73
	v_add_f32_e32 v1, v70, v1
	v_exp_f32_e32 v74, v74
	v_add_f32_e32 v1, v71, v1
	v_exp_f32_e32 v75, v75
	v_add_f32_e32 v1, v72, v1
	v_exp_f32_e32 v76, v76
	v_add_f32_e32 v1, v73, v1
	v_exp_f32_e32 v77, v77
	v_add_f32_e32 v1, v74, v1
	v_exp_f32_e32 v78, v78
	v_add_f32_e32 v1, v75, v1
	v_exp_f32_e32 v79, v79
	v_add_f32_e32 v1, v76, v1
	v_exp_f32_e32 v80, v80
	v_add_f32_e32 v1, v77, v1
	v_exp_f32_e32 v81, v81
	v_add_f32_e32 v1, v78, v1
	v_exp_f32_e32 v82, v82
	v_add_f32_e32 v1, v79, v1
	v_exp_f32_e32 v83, v83
	v_add_f32_e32 v1, v80, v1
	v_exp_f32_e32 v84, v84
	v_add_f32_e32 v1, v81, v1
	v_exp_f32_e32 v85, v85
	v_add_f32_e32 v1, v82, v1
	v_exp_f32_e32 v86, v86
	v_add_f32_e32 v1, v83, v1
	v_exp_f32_e32 v87, v87
	v_add_f32_e32 v1, v84, v1
	v_exp_f32_e32 v88, v88
	v_add_f32_e32 v1, v85, v1
	v_exp_f32_e32 v89, v89
	v_add_f32_e32 v1, v86, v1
	v_exp_f32_e32 v90, v90
	v_add_f32_e32 v1, v87, v1
	v_exp_f32_e32 v91, v91
	v_add_f32_e32 v1, v88, v1
	v_exp_f32_e32 v92, v92
	v_add_f32_e32 v1, v89, v1
	v_exp_f32_e32 v93, v93
	v_add_f32_e32 v1, v90, v1
	v_exp_f32_e32 v94, v94
	v_add_f32_e32 v1, v91, v1
	v_exp_f32_e32 v95, v95
	v_add_f32_e32 v1, v92, v1
	v_exp_f32_e32 v96, v96
	v_add_f32_e32 v1, v93, v1
	v_exp_f32_e32 v97, v97
	v_add_f32_e32 v1, v94, v1
	v_add_f32_e32 v1, v95, v1
	v_add_f32_e32 v1, v96, v1
	v_add_f32_e32 v226, v97, v1
	v_add_f32_e32 v219, v219, v226

; #define LAS __attribute__((address_space(3)))
; #define MFMA32(a, b, c) __builtin_amdgcn_mfma_f32_32x32x16_bf16((a), (b), (c), 0, 0, 0)
; DI void attn_unit(const bf16_t* Q, const bf16_t* Kp, const bf16_t* Vp, bf16_t* O, size_t qrow0, size_t krow0, int ntile, int h, float lam, float lam_init, const float* gsub, LAS unsigned char* lds) {
;     ...
;         for (int kh = 0; kh < 2; ++kh)
; #pragma unroll
;     ...
;       {
;         const int t1 = t + 1;
;         { const int tk = (t1 + 4 < ntile) ? t1 + 4 : ntile - 1; AT_ISSUE_K(tk, ks0); const int tv = (t1 + 2 < ntile) ? t1 + 2 : ntile - 1; AT_ISSUE_V(tv, vs1); }
;         LAS unsigned char* kb = lds + KRING + ks1 * SLOT + kro;
;         LAS unsigned char* vb = lds + VRING + vsm1 * SLOT + vro;
;         __builtin_amdgcn_s_setprio(1);
;         { bf16x8 ql[4];
; #pragma unroll
;           for (int d0 = 0; d0 < 4; ++d0) ql[d0] = qf[d0];
; #pragma unroll
;           for (int kh = 0; kh < 2; ++kh) {
;             bf16x8 kf[4];
; #pragma unroll
;             for (int e = 0; e < 4; ++e) kf[e] = *(const LAS bf16x8*)(kb + kh * 4096 + (((2 * e + hh) ^ ksw) * 16));
;             sc[kh] = MFMA32(kf[0], ql[0], negm);
; #pragma unroll
;             for (int d0 = 1; d0 < 4; ++d0) sc[kh] = MFMA32(kf[d0], ql[d0], sc[kh]);
;             __builtin_amdgcn_sched_barrier(0);
;           } }
; #pragma unroll
;         for (int j = 0; j < 4; ++j) {
;             s16x4 lo[4], hi[4];
; #pragma unroll
;             for (int e = 0; e < 4; ++e) { LAS unsigned char* vp = vb + j * 4096 + ((e ^ q4) * 64);
;                 lo[e] = __builtin_bit_cast(s16x4, __builtin_amdgcn_ds_read_tr16_b64_v4i16((LAS s16x4*)vp));
;                 hi[e] = __builtin_bit_cast(s16x4, __builtin_amdgcn_ds_read_tr16_b64_v4i16((LAS s16x4*)(vp + 2048))); }
; #pragma unroll
;             for (int e = 0; e < 4; ++e) ot[e] = MFMA32(__builtin_shufflevector(lo[e], hi[e], 0, 1, 2, 3, 4, 5, 6, 7), __builtin_bit_cast(bf16x8, pp[j]), ot[e]);
;             __builtin_amdgcn_sched_barrier(0);
;         }
;         __builtin_amdgcn_s_setprio(0);
;         if (!shifted) {
;             ps = 0.f;
; #pragma unroll
;             for (int kh = 0; kh < 2; ++kh)
; #pragma unroll
;                 for (int i = 0; i < 16; ++i) { sn[kh][i] = __builtin_amdgcn_exp2f(sn[kh][i]); ps += sn[kh][i]; }
;             l_run += ps;
;         }
.LBB0_557:
	s_add_i32 s77, s76, s66
	s_add_i32 s76, s76, s69
	s_add_i32 s77, s77, 0
	s_mov_b32 m0, s77
	s_nop 0
	global_load_lds_dwordx4 v[198:199], off
	s_add_i32 s76, s76, 0
	s_addk_i32 s74, 0x4000
	s_mov_b32 m0, s76
	s_nop 0
	global_load_lds_dwordx4 v[200:201], off
	s_or_b32 s76, s74, 0x10000
	s_add_i32 s76, s76, s66
	s_or_b32 s74, s74, 0x12000
	s_add_i32 s76, s76, 0
	s_mov_b32 m0, s76
	s_nop 0
	global_load_lds_dwordx4 v[202:203], off
	s_add_i32 s74, s74, s66
	s_add_i32 s74, s74, 0
	s_mov_b32 m0, s74
	s_nop 0
	global_load_lds_dwordx4 v[204:205], off
	s_add_i32 s73, s72, 1
	s_and_b32 s73, s73, 3
	s_addk_i32 s75, 0x4000
	v_cvt_pk_bf16_f32 v166, v66, v67
	v_cvt_pk_bf16_f32 v167, v68, v69
	v_cvt_pk_bf16_f32 v168, v70, v71
	v_cvt_pk_bf16_f32 v169, v72, v73
	v_cvt_pk_bf16_f32 v170, v74, v75
	v_cvt_pk_bf16_f32 v171, v76, v77
	v_cvt_pk_bf16_f32 v172, v78, v79
	v_cvt_pk_bf16_f32 v173, v80, v81
	v_cvt_pk_bf16_f32 v174, v82, v83
	v_cvt_pk_bf16_f32 v175, v84, v85
	v_cvt_pk_bf16_f32 v176, v86, v87
	v_cvt_pk_bf16_f32 v177, v88, v89
	v_cvt_pk_bf16_f32 v162, v90, v91
	v_cvt_pk_bf16_f32 v163, v92, v93
	v_cvt_pk_bf16_f32 v164, v94, v95
	v_cvt_pk_bf16_f32 v165, v96, v97
	s_and_b32 s74, s75, 0xc000
	s_setprio 1
	v_lshl_add_u32 v1, s73, 14, v213
	v_add_u32_e32 v86, v1, v214
	ds_read_b128 v[82:85], v86
	v_add_u32_e32 v207, v1, v215
	v_add_u32_e32 v227, v1, v216
	v_add_u32_e32 v1, v1, v217
	s_waitcnt lgkmcnt(0)
	v_mfma_f32_32x32x16_bf16 v[66:81], v[82:85], v[146:149], v[98:113]
	ds_read_b128 v[82:85], v207
	s_waitcnt lgkmcnt(0)
	v_mfma_f32_32x32x16_bf16 v[66:81], v[82:85], v[150:153], v[66:81]
	ds_read_b128 v[82:85], v227
	s_waitcnt lgkmcnt(0)
	v_mfma_f32_32x32x16_bf16 v[66:81], v[82:85], v[154:157], v[66:81]
	ds_read_b128 v[82:85], v1
	s_waitcnt lgkmcnt(0)
	v_mfma_f32_32x32x16_bf16 v[66:81], v[82:85], v[158:161], v[66:81]
	ds_read_b128 v[182:185], v86 offset:4096
	s_waitcnt lgkmcnt(0)
	v_mfma_f32_32x32x16_bf16 v[82:97], v[182:185], v[146:149], v[98:113]
	ds_read_b128 v[182:185], v207 offset:4096
	s_waitcnt lgkmcnt(0)
	v_mfma_f32_32x32x16_bf16 v[82:97], v[182:185], v[150:153], v[82:97]
	ds_read_b128 v[182:185], v227 offset:4096
	s_waitcnt lgkmcnt(0)
	v_mfma_f32_32x32x16_bf16 v[82:97], v[182:185], v[154:157], v[82:97]
	ds_read_b128 v[182:185], v1 offset:4096
	s_waitcnt lgkmcnt(0)
	v_mfma_f32_32x32x16_bf16 v[82:97], v[182:185], v[158:161], v[82:97]
	v_add_u32_e32 v1, s74, v225
	v_add_u32_e32 v207, v1, v224
	v_add_u32_e32 v227, v1, v223
	ds_read_b64_tr_b16 v[182:183], v207
	ds_read_b64_tr_b16 v[184:185], v207 offset:2048
	ds_read_b64_tr_b16 v[228:229], v227
	ds_read_b64_tr_b16 v[230:231], v227 offset:2048
	v_add_u32_e32 v232, v1, v222
	v_add_u32_e32 v1, v1, v220
	s_waitcnt lgkmcnt(2)
	v_mfma_f32_32x32x16_bf16 v[50:65], v[182:185], v[166:169], v[50:65]
	ds_read_b64_tr_b16 v[182:183], v232
	ds_read_b64_tr_b16 v[184:185], v232 offset:2048
	s_waitcnt lgkmcnt(2)
	v_mfma_f32_32x32x16_bf16 v[34:49], v[228:231], v[166:169], v[34:49]
	ds_read_b64_tr_b16 v[228:229], v1
	ds_read_b64_tr_b16 v[230:231], v1 offset:2048
	s_waitcnt lgkmcnt(2)
	v_mfma_f32_32x32x16_bf16 v[18:33], v[182:185], v[166:169], v[18:33]
	s_waitcnt lgkmcnt(0)
	v_mfma_f32_32x32x16_bf16 v[2:17], v[228:231], v[166:169], v[2:17]
	ds_read_b64_tr_b16 v[166:167], v207 offset:4096
	ds_read_b64_tr_b16 v[168:169], v207 offset:6144
	ds_read_b64_tr_b16 v[182:183], v227 offset:4096
	ds_read_b64_tr_b16 v[184:185], v227 offset:6144
	s_waitcnt lgkmcnt(2)
	v_mfma_f32_32x32x16_bf16 v[50:65], v[166:169], v[170:173], v[50:65]
	s_waitcnt lgkmcnt(0)
	v_mfma_f32_32x32x16_bf16 v[34:49], v[182:185], v[170:173], v[34:49]
	ds_read_b64_tr_b16 v[166:167], v232 offset:4096
	ds_read_b64_tr_b16 v[168:169], v232 offset:6144
	ds_read_b64_tr_b16 v[182:183], v1 offset:4096
	ds_read_b64_tr_b16 v[184:185], v1 offset:6144
	s_waitcnt lgkmcnt(2)
	v_mfma_f32_32x32x16_bf16 v[18:33], v[166:169], v[170:173], v[18:33]
	s_waitcnt lgkmcnt(0)
	v_mfma_f32_32x32x16_bf16 v[2:17], v[182:185], v[170:173], v[2:17]
	ds_read_b64_tr_b16 v[166:167], v207 offset:8192
	ds_read_b64_tr_b16 v[168:169], v207 offset:10240
	ds_read_b64_tr_b16 v[170:171], v227 offset:8192
	ds_read_b64_tr_b16 v[172:173], v227 offset:10240
	s_waitcnt lgkmcnt(2)
	v_mfma_f32_32x32x16_bf16 v[50:65], v[166:169], v[174:177], v[50:65]
	s_waitcnt lgkmcnt(0)
	v_mfma_f32_32x32x16_bf16 v[34:49], v[170:173], v[174:177], v[34:49]
	ds_read_b64_tr_b16 v[166:167], v232 offset:8192
	ds_read_b64_tr_b16 v[168:169], v232 offset:10240
	ds_read_b64_tr_b16 v[170:171], v1 offset:8192
	ds_read_b64_tr_b16 v[172:173], v1 offset:10240
	s_waitcnt lgkmcnt(2)
	v_mfma_f32_32x32x16_bf16 v[18:33], v[166:169], v[174:177], v[18:33]
	s_waitcnt lgkmcnt(0)
	v_mfma_f32_32x32x16_bf16 v[2:17], v[170:173], v[174:177], v[2:17]
	ds_read_b64_tr_b16 v[166:167], v207 offset:12288
	ds_read_b64_tr_b16 v[168:169], v207 offset:14336
	ds_read_b64_tr_b16 v[170:171], v227 offset:12288
	ds_read_b64_tr_b16 v[172:173], v227 offset:14336
	s_waitcnt lgkmcnt(2)
	v_mfma_f32_32x32x16_bf16 v[50:65], v[166:169], v[162:165], v[50:65]
	s_waitcnt lgkmcnt(0)
	v_mfma_f32_32x32x16_bf16 v[34:49], v[170:173], v[162:165], v[34:49]
	ds_read_b64_tr_b16 v[166:167], v232 offset:12288
	ds_read_b64_tr_b16 v[168:169], v232 offset:14336
	ds_read_b64_tr_b16 v[170:171], v1 offset:12288
	ds_read_b64_tr_b16 v[172:173], v1 offset:14336
	s_waitcnt lgkmcnt(2)
	v_mfma_f32_32x32x16_bf16 v[18:33], v[166:169], v[162:165], v[18:33]
	s_waitcnt lgkmcnt(0)
	v_mfma_f32_32x32x16_bf16 v[2:17], v[170:173], v[162:165], v[2:17]
	s_setprio 0
	s_and_b64 vcc, exec, s[40:41]
	s_cbranch_vccnz .LBB0_559
; DI void attn_unit(const bf16_t* Q, const bf16_t* Kp, const bf16_t* Vp, bf16_t* O, size_t qrow0, size_t krow0, int ntile, int h, float lam, float lam_init, const float* gsub, LAS unsigned char* lds) {
;     ...
;         if (!shifted) {
;             ps = 0.f;
; #pragma unroll
;             for (int kh = 0; kh < 2; ++kh)
; #pragma unroll
;                 for (int i = 0; i < 16; ++i) { sn[kh][i] = __builtin_amdgcn_exp2f(sn[kh][i]); ps += sn[kh][i]; }
;             l_run += ps;
;         }
	v_exp_f32_e32 v114, v114
	v_exp_f32_e32 v115, v115
	v_exp_f32_e32 v116, v116
	v_exp_f32_e32 v117, v117
	v_add_f32_e32 v1, 0, v114
	v_exp_f32_e32 v118, v118
	v_add_f32_e32 v1, v115, v1
	v_exp_f32_e32 v119, v119
	v_add_f32_e32 v1, v116, v1
	v_exp_f32_e32 v120, v120
	v_add_f32_e32 v1, v117, v1
	v_exp_f32_e32 v121, v121
	v_add_f32_e32 v1, v118, v1
	v_exp_f32_e32 v122, v122
	v_add_f32_e32 v1, v119, v1
	v_exp_f32_e32 v123, v123
	v_add_f32_e32 v1, v120, v1
	v_exp_f32_e32 v124, v124
	v_add_f32_e32 v1, v121, v1
	v_exp_f32_e32 v125, v125
	v_add_f32_e32 v1, v122, v1
	v_exp_f32_e32 v126, v126
	v_add_f32_e32 v1, v123, v1
	v_exp_f32_e32 v127, v127
	v_add_f32_e32 v1, v124, v1
	v_exp_f32_e32 v128, v128
	v_add_f32_e32 v1, v125, v1
	v_exp_f32_e32 v129, v129
	v_add_f32_e32 v1, v126, v1
	v_exp_f32_e32 v130, v130
	v_add_f32_e32 v1, v127, v1
	v_exp_f32_e32 v131, v131
	v_add_f32_e32 v1, v128, v1
	v_exp_f32_e32 v132, v132
	v_add_f32_e32 v1, v129, v1
	v_exp_f32_e32 v133, v133
	v_add_f32_e32 v1, v130, v1
	v_exp_f32_e32 v134, v134
	v_add_f32_e32 v1, v131, v1
	v_exp_f32_e32 v135, v135
	v_add_f32_e32 v1, v132, v1
	v_exp_f32_e32 v136, v136
	v_add_f32_e32 v1, v133, v1
	v_exp_f32_e32 v137, v137
	v_add_f32_e32 v1, v134, v1
	v_exp_f32_e32 v138, v138
	v_add_f32_e32 v1, v135, v1
	v_exp_f32_e32 v139, v139
	v_add_f32_e32 v1, v136, v1
	v_exp_f32_e32 v140, v140
	v_add_f32_e32 v1, v137, v1
	v_exp_f32_e32 v141, v141
	v_add_f32_e32 v1, v138, v1
	v_exp_f32_e32 v142, v142
	v_add_f32_e32 v1, v139, v1
	v_exp_f32_e32 v143, v143
	v_add_f32_e32 v1, v140, v1
	v_exp_f32_e32 v144, v144
	v_add_f32_e32 v1, v141, v1
	v_exp_f32_e32 v145, v145
	v_add_f32_e32 v1, v142, v1
	v_add_f32_e32 v1, v143, v1
	v_add_f32_e32 v1, v144, v1
	v_add_f32_e32 v226, v145, v1
	v_add_f32_e32 v219, v219, v226
